# NA loop: second score accumulator takes the running-max tuple as C operand directly (8 copies removed)
# speedup vs baseline: 1.0147x; 1.0025x over previous
.LBB0_515:
	s_xor_b64 s[82:83], s[88:89], -1
	s_and_b32 s94, s33, 1
	s_cmp_lt_i32 s33, s40
	s_cselect_b64 s[76:77], -1, 0
	s_cmp_ge_i32 s33, s40
	s_cselect_b64 s[90:91], -1, 0
	s_add_i32 s0, s41, s33
	v_cmp_ge_i32_e32 vcc, s0, v206
	v_cmp_lt_i32_e64 s[0:1], s0, v207
	s_and_b64 s[0:1], vcc, s[0:1]
	s_or_b64 s[90:91], s[90:91], s[0:1]
	s_and_saveexec_b64 s[0:1], s[90:91]
	s_cbranch_execz .LBB0_588
	s_mul_i32 s33, s94, 0x3400
	v_add_u32_e32 v52, s33, v209
	ds_read_b128 v[48:51], v52
	ds_read_b128 v[80:83], v52 offset:32
	ds_read_b128 v[84:87], v52 offset:6656
	ds_read_b128 v[88:91], v52 offset:6688
	ds_read_b128 v[92:95], v52 offset:64
	ds_read_b128 v[96:99], v52 offset:96
	ds_read_b128 v[100:103], v52 offset:6720
	ds_read_b128 v[104:107], v52 offset:6752
	s_waitcnt lgkmcnt(0)
	v_mfma_f32_32x32x16_bf16 v[64:79], v[48:51], v[114:117], v[32:47]
	v_mfma_f32_32x32x16_bf16 v[64:79], v[80:83], v[118:121], v[64:79]
	s_mul_i32 s33, s94, 0x2400
	v_add_u32_e32 v80, s33, v210
	ds_read_b128 v[166:169], v80 offset:26624
	ds_read_b128 v[158:161], v80 offset:26656
	ds_read_b128 v[162:165], v80 offset:31232
	ds_read_b128 v[154:157], v80 offset:31264
	ds_read_b128 v[150:153], v80 offset:26688
	ds_read_b128 v[146:149], v80 offset:31296
	ds_read_b128 v[142:145], v80 offset:26720
	ds_read_b128 v[138:141], v80 offset:31328
	v_mfma_f32_32x32x16_bf16 v[48:63], v[84:87], v[114:117], v[32:47]
	v_mfma_f32_32x32x16_bf16 v[48:63], v[88:91], v[118:121], v[48:63]
	v_mfma_f32_32x32x16_bf16 v[64:79], v[92:95], v[122:125], v[64:79]
	v_mfma_f32_32x32x16_bf16 v[48:63], v[100:103], v[122:125], v[48:63]
	v_mfma_f32_32x32x16_bf16 v[64:79], v[96:99], v[126:129], v[64:79]
	v_mfma_f32_32x32x16_bf16 v[48:63], v[104:107], v[126:129], v[48:63]
	s_andn2_b64 vcc, exec, s[76:77]
	s_cbranch_vccnz .LBB0_582
	ds_read2_b32 v[80:81], v211 offset1:32
	ds_read2_b32 v[82:83], v211 offset0:1 offset1:33
	ds_read2_b32 v[84:85], v211 offset0:2 offset1:34
	ds_read2_b32 v[86:87], v211 offset0:3 offset1:35
	ds_read2_b32 v[88:89], v211 offset0:8 offset1:40
	ds_read2_b32 v[90:91], v211 offset0:9 offset1:41
	ds_read2_b32 v[92:93], v211 offset0:10 offset1:42
	ds_read2_b32 v[94:95], v211 offset0:11 offset1:43
	ds_read2_b32 v[96:97], v211 offset0:16 offset1:48
	ds_read2_b32 v[98:99], v211 offset0:17 offset1:49
	ds_read2_b32 v[100:101], v211 offset0:18 offset1:50
	ds_read2_b32 v[102:103], v211 offset0:19 offset1:51
	ds_read2_b32 v[104:105], v211 offset0:24 offset1:56
	ds_read2_b32 v[106:107], v211 offset0:25 offset1:57
	ds_read2_b32 v[108:109], v211 offset0:26 offset1:58
	ds_read2_b32 v[110:111], v211 offset0:27 offset1:59
	s_waitcnt lgkmcnt(0)
	v_add_f32_e32 v64, v64, v80
	v_mov_b32_e32 v80, 0xff800000
	v_cndmask_b32_e64 v64, v80, v64, s[10:11]
	v_add_f32_e32 v48, v48, v81
	v_cndmask_b32_e64 v48, v80, v48, s[12:13]
	v_add_f32_e32 v65, v65, v82
	v_cndmask_b32_e64 v65, v80, v65, s[14:15]
	v_add_f32_e32 v49, v49, v83
	v_cndmask_b32_e64 v49, v80, v49, s[16:17]
	v_add_f32_e32 v66, v66, v84
	v_cndmask_b32_e64 v66, v80, v66, s[18:19]
	v_add_f32_e32 v50, v50, v85
	v_cndmask_b32_e64 v50, v80, v50, s[20:21]
	v_add_f32_e32 v67, v67, v86
	v_cndmask_b32_e64 v67, v80, v67, s[22:23]
	v_add_f32_e32 v51, v51, v87
	v_cndmask_b32_e64 v51, v80, v51, s[24:25]
	v_add_f32_e32 v68, v68, v88
	v_cndmask_b32_e64 v68, v80, v68, s[26:27]
	v_add_f32_e32 v52, v52, v89
	v_cndmask_b32_e64 v52, v80, v52, s[28:29]
	v_add_f32_e32 v69, v69, v90
	v_cndmask_b32_e64 v69, v80, v69, s[30:31]
	v_add_f32_e32 v53, v53, v91
	v_cndmask_b32_e64 v53, v80, v53, s[34:35]
	v_add_f32_e32 v70, v70, v92
	v_cndmask_b32_e64 v70, v80, v70, s[36:37]
	v_add_f32_e32 v54, v54, v93
	v_cndmask_b32_e64 v54, v80, v54, s[8:9]
	v_add_f32_e32 v71, v71, v94
	v_cndmask_b32_e64 v71, v80, v71, s[4:5]
	v_add_f32_e32 v55, v55, v95
	v_cndmask_b32_e64 v55, v80, v55, s[42:43]
	v_add_f32_e32 v72, v72, v96
	v_cndmask_b32_e64 v72, v80, v72, s[44:45]
	v_add_f32_e32 v56, v56, v97
	v_cndmask_b32_e64 v56, v80, v56, s[46:47]
	v_add_f32_e32 v73, v73, v98
	v_cndmask_b32_e64 v73, v80, v73, s[48:49]
	v_add_f32_e32 v57, v57, v99
	v_cndmask_b32_e64 v57, v80, v57, s[50:51]
	v_add_f32_e32 v74, v74, v100
	v_cndmask_b32_e64 v74, v80, v74, s[52:53]
	v_add_f32_e32 v58, v58, v101
	v_cndmask_b32_e64 v58, v80, v58, s[54:55]
	v_add_f32_e32 v75, v75, v102
	v_cndmask_b32_e64 v75, v80, v75, s[56:57]
	v_add_f32_e32 v59, v59, v103
	v_cndmask_b32_e64 v59, v80, v59, s[58:59]
	v_add_f32_e32 v76, v76, v104
	v_cndmask_b32_e64 v76, v80, v76, s[60:61]
	v_add_f32_e32 v60, v60, v105
	v_cndmask_b32_e64 v60, v80, v60, s[62:63]
	v_add_f32_e32 v77, v77, v106
	v_cndmask_b32_e64 v77, v80, v77, s[64:65]
	v_add_f32_e32 v61, v61, v107
	v_cndmask_b32_e64 v61, v80, v61, s[66:67]
	v_add_f32_e32 v78, v78, v108
	v_cndmask_b32_e64 v78, v80, v78, s[68:69]
	v_add_f32_e32 v62, v62, v109
	v_cndmask_b32_e64 v62, v80, v62, s[70:71]
	v_add_f32_e32 v79, v79, v110
	v_cndmask_b32_e64 v79, v80, v79, s[72:73]
	v_add_f32_e32 v63, v63, v111
	v_cndmask_b32_e64 v63, v80, v63, s[74:75]

.LBB0_652:
	s_mov_b64 s[2:3], exec
	v_readlane_b32 s36, v253, 51
	v_readlane_b32 s48, v253, 63
	v_readlane_b32 s49, v254, 0
	s_mov_b32 s41, 0xffff
	s_movk_i32 s40, 0x1fff
	s_movk_i32 s39, 0x4200
	v_readlane_b32 s38, v253, 49
	v_readlane_b32 s37, v253, 52
	v_readlane_b32 s42, v253, 57
	v_readlane_b32 s43, v253, 58
	v_readlane_b32 s44, v253, 59
	v_readlane_b32 s45, v253, 60
	v_readlane_b32 s46, v253, 61
	v_readlane_b32 s47, v253, 62
	v_readlane_b32 s50, v254, 1
	v_readlane_b32 s51, v254, 2
	v_and_b32_e32 v32, 15, v104
	v_lshrrev_b32_e32 v33, 4, v104
	v_or3_b32 v112, v198, s19, v32
	v_lshl_add_u64 v[34:35], v[112:113], 2, s[48:49]
	global_load_dword v96, v[34:35], off
	v_lshlrev_b32_e32 v36, 2, v196
	v_lshl_add_u32 v36, v33, 5, v36
	v_mul_u32_u24_e32 v36, 0x3800, v36
	v_lshl_add_u32 v36, v32, 1, v36
	v_readfirstlane_b32 s4, v106
	v_readfirstlane_b32 s5, v107
	v_mov_b32_e32 v40, v36
	v_add_u32_e32 v41, 0x3800, v36
	v_add_u32_e32 v42, 0x7000, v36
	v_add_u32_e32 v43, 0xa800, v36
	v_add_u32_e32 v44, 0x1c000, v36
	v_add_u32_e32 v45, 0x1f800, v36
	v_add_u32_e32 v46, 0x23000, v36
	v_add_u32_e32 v47, 0x26800, v36
	v_add_u32_e32 v48, 0x38000, v36
	v_add_u32_e32 v49, 0x3b800, v36
	v_add_u32_e32 v50, 0x3f000, v36
	v_add_u32_e32 v51, 0x42800, v36
	v_add_u32_e32 v52, 0x54000, v36
	v_add_u32_e32 v53, 0x57800, v36
	v_add_u32_e32 v54, 0x5b000, v36
	v_add_u32_e32 v55, 0x5e800, v36
	v_permlane16_swap_b32_e32 v0, v16
	v_permlane16_swap_b32_e32 v1, v17
	v_permlane16_swap_b32_e32 v2, v18
	v_permlane16_swap_b32_e32 v3, v19
	v_permlane16_swap_b32_e32 v4, v20
	v_permlane16_swap_b32_e32 v5, v21
	v_permlane16_swap_b32_e32 v6, v22
	v_permlane16_swap_b32_e32 v7, v23
	v_permlane16_swap_b32_e32 v8, v24
	v_permlane16_swap_b32_e32 v9, v25
	v_permlane16_swap_b32_e32 v10, v26
	v_permlane16_swap_b32_e32 v11, v27
	v_permlane16_swap_b32_e32 v12, v28
	v_permlane16_swap_b32_e32 v13, v29
	v_permlane16_swap_b32_e32 v14, v30
	v_permlane16_swap_b32_e32 v15, v31
	global_load_ushort v56, v40, s[4:5]
	global_load_ushort v57, v41, s[4:5]
	global_load_ushort v58, v42, s[4:5]
	global_load_ushort v59, v43, s[4:5]
	global_load_ushort v60, v44, s[4:5]
	global_load_ushort v61, v45, s[4:5]
	global_load_ushort v62, v46, s[4:5]
	global_load_ushort v63, v47, s[4:5]
	global_load_ushort v64, v48, s[4:5]
	global_load_ushort v65, v49, s[4:5]
	global_load_ushort v66, v50, s[4:5]
	global_load_ushort v67, v51, s[4:5]
	global_load_ushort v68, v52, s[4:5]
	global_load_ushort v69, v53, s[4:5]
	global_load_ushort v70, v54, s[4:5]
	global_load_ushort v71, v55, s[4:5]
	s_waitcnt vmcnt(0)
	v_lshlrev_b32_e32 v56, 16, v56
	v_lshlrev_b32_e32 v57, 16, v57
	v_fmac_f32_e32 v0, v96, v56
	v_fmac_f32_e32 v1, v96, v57
	v_mul_f32_e32 v72, 0x3d372713, v0
	v_mul_f32_e32 v73, 0x3d372713, v1
	v_mul_f32_e32 v72, v0, v72
	v_mul_f32_e32 v73, v1, v73
	v_fma_f32 v72, v0, v72, v0
	v_fma_f32 v73, v1, v73, v1
	v_mul_f32_e32 v72, 0x3f4c422a, v72
	v_mul_f32_e32 v73, 0x3f4c422a, v73
	v_mul_f32_e32 v72, -2.0, v72
	v_mul_f32_e32 v73, -2.0, v73
	v_mul_f32_e32 v72, 0x3fb8aa3b, v72
	v_mul_f32_e32 v73, 0x3fb8aa3b, v73
	v_exp_f32_e32 v72, v72
	v_exp_f32_e32 v73, v73
	v_add_f32_e32 v72, 1.0, v72
	v_add_f32_e32 v73, 1.0, v73
	v_rcp_f32_e32 v72, v72
	v_rcp_f32_e32 v73, v73
	v_mul_f32_e32 v0, v0, v72
	v_mul_f32_e32 v1, v1, v73
	v_bfe_u32 v72, v0, 16, 1
	v_bfe_u32 v73, v1, 16, 1
	v_add3_u32 v0, v0, v72, s33
	v_add3_u32 v1, v1, v73, s33
	global_store_short_d16_hi v40, v0, s[4:5]
	global_store_short_d16_hi v41, v1, s[4:5]
	v_lshlrev_b32_e32 v58, 16, v58
	v_lshlrev_b32_e32 v59, 16, v59
	v_fmac_f32_e32 v2, v96, v58
	v_fmac_f32_e32 v3, v96, v59
	v_mul_f32_e32 v72, 0x3d372713, v2
	v_mul_f32_e32 v73, 0x3d372713, v3
	v_mul_f32_e32 v72, v2, v72
	v_mul_f32_e32 v73, v3, v73
	v_fma_f32 v72, v2, v72, v2
	v_fma_f32 v73, v3, v73, v3
	v_mul_f32_e32 v72, 0x3f4c422a, v72
	v_mul_f32_e32 v73, 0x3f4c422a, v73
	v_mul_f32_e32 v72, -2.0, v72
	v_mul_f32_e32 v73, -2.0, v73
	v_mul_f32_e32 v72, 0x3fb8aa3b, v72
	v_mul_f32_e32 v73, 0x3fb8aa3b, v73
	v_exp_f32_e32 v72, v72
	v_exp_f32_e32 v73, v73
	v_add_f32_e32 v72, 1.0, v72
	v_add_f32_e32 v73, 1.0, v73
	v_rcp_f32_e32 v72, v72
	v_rcp_f32_e32 v73, v73
	v_mul_f32_e32 v2, v2, v72
	v_mul_f32_e32 v3, v3, v73
	v_bfe_u32 v72, v2, 16, 1
	v_bfe_u32 v73, v3, 16, 1
	v_add3_u32 v2, v2, v72, s33
	v_add3_u32 v3, v3, v73, s33
	global_store_short_d16_hi v42, v2, s[4:5]
	global_store_short_d16_hi v43, v3, s[4:5]
	v_lshlrev_b32_e32 v60, 16, v60
	v_lshlrev_b32_e32 v61, 16, v61
	v_fmac_f32_e32 v4, v96, v60
	v_fmac_f32_e32 v5, v96, v61
	v_mul_f32_e32 v72, 0x3d372713, v4
	v_mul_f32_e32 v73, 0x3d372713, v5
	v_mul_f32_e32 v72, v4, v72
	v_mul_f32_e32 v73, v5, v73
	v_fma_f32 v72, v4, v72, v4
	v_fma_f32 v73, v5, v73, v5
	v_mul_f32_e32 v72, 0x3f4c422a, v72
	v_mul_f32_e32 v73, 0x3f4c422a, v73
	v_mul_f32_e32 v72, -2.0, v72
	v_mul_f32_e32 v73, -2.0, v73
	v_mul_f32_e32 v72, 0x3fb8aa3b, v72
	v_mul_f32_e32 v73, 0x3fb8aa3b, v73
	v_exp_f32_e32 v72, v72
	v_exp_f32_e32 v73, v73
	v_add_f32_e32 v72, 1.0, v72
	v_add_f32_e32 v73, 1.0, v73
	v_rcp_f32_e32 v72, v72
	v_rcp_f32_e32 v73, v73
	v_mul_f32_e32 v4, v4, v72
	v_mul_f32_e32 v5, v5, v73
	v_bfe_u32 v72, v4, 16, 1
	v_bfe_u32 v73, v5, 16, 1
	v_add3_u32 v4, v4, v72, s33
	v_add3_u32 v5, v5, v73, s33
	global_store_short_d16_hi v44, v4, s[4:5]
	global_store_short_d16_hi v45, v5, s[4:5]
	v_lshlrev_b32_e32 v62, 16, v62
	v_lshlrev_b32_e32 v63, 16, v63
	v_fmac_f32_e32 v6, v96, v62
	v_fmac_f32_e32 v7, v96, v63
	v_mul_f32_e32 v72, 0x3d372713, v6
	v_mul_f32_e32 v73, 0x3d372713, v7
	v_mul_f32_e32 v72, v6, v72
	v_mul_f32_e32 v73, v7, v73
	v_fma_f32 v72, v6, v72, v6
	v_fma_f32 v73, v7, v73, v7
	v_mul_f32_e32 v72, 0x3f4c422a, v72
	v_mul_f32_e32 v73, 0x3f4c422a, v73
	v_mul_f32_e32 v72, -2.0, v72
	v_mul_f32_e32 v73, -2.0, v73
	v_mul_f32_e32 v72, 0x3fb8aa3b, v72
	v_mul_f32_e32 v73, 0x3fb8aa3b, v73
	v_exp_f32_e32 v72, v72
	v_exp_f32_e32 v73, v73
	v_add_f32_e32 v72, 1.0, v72
	v_add_f32_e32 v73, 1.0, v73
	v_rcp_f32_e32 v72, v72
	v_rcp_f32_e32 v73, v73
	v_mul_f32_e32 v6, v6, v72
	v_mul_f32_e32 v7, v7, v73
	v_bfe_u32 v72, v6, 16, 1
	v_bfe_u32 v73, v7, 16, 1
	v_add3_u32 v6, v6, v72, s33
	v_add3_u32 v7, v7, v73, s33
	global_store_short_d16_hi v46, v6, s[4:5]
	global_store_short_d16_hi v47, v7, s[4:5]
	v_lshlrev_b32_e32 v64, 16, v64
	v_lshlrev_b32_e32 v65, 16, v65
	v_fmac_f32_e32 v8, v96, v64
	v_fmac_f32_e32 v9, v96, v65
	v_mul_f32_e32 v72, 0x3d372713, v8
	v_mul_f32_e32 v73, 0x3d372713, v9
	v_mul_f32_e32 v72, v8, v72
	v_mul_f32_e32 v73, v9, v73
	v_fma_f32 v72, v8, v72, v8
	v_fma_f32 v73, v9, v73, v9
	v_mul_f32_e32 v72, 0x3f4c422a, v72
	v_mul_f32_e32 v73, 0x3f4c422a, v73
	v_mul_f32_e32 v72, -2.0, v72
	v_mul_f32_e32 v73, -2.0, v73
	v_mul_f32_e32 v72, 0x3fb8aa3b, v72
	v_mul_f32_e32 v73, 0x3fb8aa3b, v73
	v_exp_f32_e32 v72, v72
	v_exp_f32_e32 v73, v73
	v_add_f32_e32 v72, 1.0, v72
	v_add_f32_e32 v73, 1.0, v73
	v_rcp_f32_e32 v72, v72
	v_rcp_f32_e32 v73, v73
	v_mul_f32_e32 v8, v8, v72
	v_mul_f32_e32 v9, v9, v73
	v_bfe_u32 v72, v8, 16, 1
	v_bfe_u32 v73, v9, 16, 1
	v_add3_u32 v8, v8, v72, s33
	v_add3_u32 v9, v9, v73, s33
	global_store_short_d16_hi v48, v8, s[4:5]
	global_store_short_d16_hi v49, v9, s[4:5]
	v_lshlrev_b32_e32 v66, 16, v66
	v_lshlrev_b32_e32 v67, 16, v67
	v_fmac_f32_e32 v10, v96, v66
	v_fmac_f32_e32 v11, v96, v67
	v_mul_f32_e32 v72, 0x3d372713, v10
	v_mul_f32_e32 v73, 0x3d372713, v11
	v_mul_f32_e32 v72, v10, v72
	v_mul_f32_e32 v73, v11, v73
	v_fma_f32 v72, v10, v72, v10
	v_fma_f32 v73, v11, v73, v11
	v_mul_f32_e32 v72, 0x3f4c422a, v72
	v_mul_f32_e32 v73, 0x3f4c422a, v73
	v_mul_f32_e32 v72, -2.0, v72
	v_mul_f32_e32 v73, -2.0, v73
	v_mul_f32_e32 v72, 0x3fb8aa3b, v72
	v_mul_f32_e32 v73, 0x3fb8aa3b, v73
	v_exp_f32_e32 v72, v72
	v_exp_f32_e32 v73, v73
	v_add_f32_e32 v72, 1.0, v72
	v_add_f32_e32 v73, 1.0, v73
	v_rcp_f32_e32 v72, v72
	v_rcp_f32_e32 v73, v73
	v_mul_f32_e32 v10, v10, v72
	v_mul_f32_e32 v11, v11, v73
	v_bfe_u32 v72, v10, 16, 1
	v_bfe_u32 v73, v11, 16, 1
	v_add3_u32 v10, v10, v72, s33
	v_add3_u32 v11, v11, v73, s33
	global_store_short_d16_hi v50, v10, s[4:5]
	global_store_short_d16_hi v51, v11, s[4:5]
	v_lshlrev_b32_e32 v68, 16, v68
	v_lshlrev_b32_e32 v69, 16, v69
	v_fmac_f32_e32 v12, v96, v68
	v_fmac_f32_e32 v13, v96, v69
	v_mul_f32_e32 v72, 0x3d372713, v12
	v_mul_f32_e32 v73, 0x3d372713, v13
	v_mul_f32_e32 v72, v12, v72
	v_mul_f32_e32 v73, v13, v73
	v_fma_f32 v72, v12, v72, v12
	v_fma_f32 v73, v13, v73, v13
	v_mul_f32_e32 v72, 0x3f4c422a, v72
	v_mul_f32_e32 v73, 0x3f4c422a, v73
	v_mul_f32_e32 v72, -2.0, v72
	v_mul_f32_e32 v73, -2.0, v73
	v_mul_f32_e32 v72, 0x3fb8aa3b, v72
	v_mul_f32_e32 v73, 0x3fb8aa3b, v73
	v_exp_f32_e32 v72, v72
	v_exp_f32_e32 v73, v73
	v_add_f32_e32 v72, 1.0, v72
	v_add_f32_e32 v73, 1.0, v73
	v_rcp_f32_e32 v72, v72
	v_rcp_f32_e32 v73, v73
	v_mul_f32_e32 v12, v12, v72
	v_mul_f32_e32 v13, v13, v73
	v_bfe_u32 v72, v12, 16, 1
	v_bfe_u32 v73, v13, 16, 1
	v_add3_u32 v12, v12, v72, s33
	v_add3_u32 v13, v13, v73, s33
	global_store_short_d16_hi v52, v12, s[4:5]
	global_store_short_d16_hi v53, v13, s[4:5]
	v_lshlrev_b32_e32 v70, 16, v70
	v_lshlrev_b32_e32 v71, 16, v71
	v_fmac_f32_e32 v14, v96, v70
	v_fmac_f32_e32 v15, v96, v71
	v_mul_f32_e32 v72, 0x3d372713, v14
	v_mul_f32_e32 v73, 0x3d372713, v15
	v_mul_f32_e32 v72, v14, v72
	v_mul_f32_e32 v73, v15, v73
	v_fma_f32 v72, v14, v72, v14
	v_fma_f32 v73, v15, v73, v15
	v_mul_f32_e32 v72, 0x3f4c422a, v72
	v_mul_f32_e32 v73, 0x3f4c422a, v73
	v_mul_f32_e32 v72, -2.0, v72
	v_mul_f32_e32 v73, -2.0, v73
	v_mul_f32_e32 v72, 0x3fb8aa3b, v72
	v_mul_f32_e32 v73, 0x3fb8aa3b, v73
	v_exp_f32_e32 v72, v72
	v_exp_f32_e32 v73, v73
	v_add_f32_e32 v72, 1.0, v72
	v_add_f32_e32 v73, 1.0, v73
	v_rcp_f32_e32 v72, v72
	v_rcp_f32_e32 v73, v73
	v_mul_f32_e32 v14, v14, v72
	v_mul_f32_e32 v15, v15, v73
	v_bfe_u32 v72, v14, 16, 1
	v_bfe_u32 v73, v15, 16, 1
	v_add3_u32 v14, v14, v72, s33
	v_add3_u32 v15, v15, v73, s33
	global_store_short_d16_hi v54, v14, s[4:5]
	global_store_short_d16_hi v55, v15, s[4:5]
	s_branch .LBB0_639
